# GLA pass C: header loads (V pieces + q/k fragments) issued back to back with one wait
# baseline (speedup 1.0000x reference)
.LBB0_762:
	s_ashr_i32 s70, s74, 8
	s_ashr_i32 s71, s70, 31
	s_lshl_b64 s[66:67], s[70:71], 12
	s_and_b32 s3, s72, 0xfc0
	s_or_b32 s66, s66, s3
	s_mul_i32 s3, s67, 0x1800
	s_mul_hi_u32 s34, s66, 0x1800
	s_bfe_u32 s2, s74, 0x20006
	s_add_i32 s34, s34, s3
	s_mul_i32 s3, s66, 0x1800
	s_add_u32 s68, s62, s3
	s_addc_u32 s69, s63, s34
	s_lshl_b32 s56, s2, 7
	v_lshl_add_u64 v[2:3], s[68:69], 0, v[104:105]
	s_lshl_b32 s2, s2, 8
	s_mov_b32 s3, s57
	v_lshl_add_u64 v[2:3], v[2:3], 0, s[2:3]
	v_lshl_add_u64 v[30:31], v[2:3], 0, v[126:127]
	v_add_co_u32_e32 v2, vcc, s76, v30
	s_mov_b32 s2, 0x31000
	s_nop 0
	v_addc_co_u32_e32 v3, vcc, 0, v31, vcc
	v_add_co_u32_e32 v6, vcc, s77, v30
	s_nop 1
	v_addc_co_u32_e32 v7, vcc, 0, v31, vcc
	v_add_co_u32_e32 v10, vcc, s78, v30
	s_nop 1
	v_addc_co_u32_e32 v11, vcc, 0, v31, vcc
	v_add_co_u32_e32 v14, vcc, s79, v30
	s_nop 1
	v_addc_co_u32_e32 v15, vcc, 0, v31, vcc
	v_add_co_u32_e32 v18, vcc, s2, v30
	s_mov_b32 s2, 0x3d000
	s_nop 0
	v_addc_co_u32_e32 v19, vcc, 0, v31, vcc
	v_add_co_u32_e32 v22, vcc, s2, v30
	s_mov_b32 s2, 0x49000
	s_nop 0
	v_addc_co_u32_e32 v23, vcc, 0, v31, vcc
	v_add_co_u32_e32 v26, vcc, s2, v30
	s_mov_b32 s2, 0x55000
	s_nop 0
	v_addc_co_u32_e32 v27, vcc, 0, v31, vcc
	v_add_co_u32_e32 v30, vcc, s2, v30
	s_nop 1
	v_addc_co_u32_e32 v31, vcc, 0, v31, vcc
	global_load_dwordx4 v[2:5], v[2:3], off
	global_load_dwordx4 v[6:9], v[6:7], off
	global_load_dwordx4 v[10:13], v[10:11], off
	global_load_dwordx4 v[14:17], v[14:15], off
	global_load_dwordx4 v[18:21], v[18:19], off
	global_load_dwordx4 v[22:25], v[22:23], off
	global_load_dwordx4 v[26:29], v[26:27], off
	global_load_dwordx4 v[30:33], v[30:31], off
	v_mov_b32_e32 v129, v103
	v_mov_b32_e32 v131, v103
	s_mov_b64 s[2:3], 0xe00
	v_lshl_add_u64 v[150:151], s[68:69], 0, v[102:103]
	v_lshl_add_u64 v[150:151], v[150:151], 0, s[56:57]
	v_lshl_add_u64 v[152:153], v[150:151], 0, v[128:129]
	v_lshl_add_u64 v[150:151], s[68:69], 0, v[130:131]
	v_lshl_add_u64 v[150:151], v[150:151], 0, s[56:57]
	v_lshl_add_u64 v[154:155], v[150:151], 0, v[128:129]
	v_lshl_add_u64 v[156:157], v[154:155], 0, s[2:3]
	v_cndmask_b32_e64 v158, 0, 1, s[64:65]
	global_load_dwordx4 v[50:53], v[152:153], off offset:3072
	global_load_dwordx4 v[162:165], v[154:155], off offset:3584
	v_cmp_ne_u32_e64 s[34:35], 1, v158
	global_load_dwordx4 v[166:169], v[154:155], off offset:3616
	global_load_dwordx4 v[74:77], v[152:153], off offset:3104
	global_load_dwordx4 v[170:173], v[154:155], off offset:3648
	global_load_dwordx4 v[66:69], v[152:153], off offset:3136
	global_load_dwordx4 v[46:49], v[154:155], off offset:3680
	global_load_dwordx4 v[70:73], v[152:153], off offset:3168
	s_andn2_b64 vcc, exec, s[64:65]
	s_cbranch_vccnz .Lgc_noct1
	v_add_co_u32_e32 v156, vcc, 0x30000, v156
	s_nop 1
	v_addc_co_u32_e32 v157, vcc, 0, v157, vcc
	global_load_dwordx4 v[34:37], v[156:157], off
	global_load_dwordx4 v[38:41], v[156:157], off offset:32
	global_load_dwordx4 v[42:45], v[156:157], off offset:64
	global_load_dwordx4 v[54:57], v[156:157], off offset:96
.Lgc_noct1:
	s_waitcnt vmcnt(0)
	ds_write_b128 v107, v[2:5]
	ds_write_b128 v107, v[6:9] offset:512
	ds_write_b128 v107, v[10:13] offset:1024
	ds_write_b128 v107, v[14:17] offset:1536
	ds_write_b128 v107, v[18:21] offset:2048
	ds_write_b128 v107, v[22:25] offset:2560
	ds_write_b128 v107, v[26:29] offset:3072
	ds_write_b128 v107, v[30:33] offset:3584
	v_mov_b64_e32 v[2:3], v[162:163]
	v_mov_b64_e32 v[4:5], v[164:165]
	v_mov_b64_e32 v[18:19], v[166:167]
	v_mov_b64_e32 v[20:21], v[168:169]
	v_mov_b64_e32 v[22:23], v[170:171]
	v_mov_b64_e32 v[24:25], v[172:173]
	s_andn2_b64 vcc, exec, s[64:65]
	s_cbranch_vccz .Lgc_ct2
	v_mov_b64_e32 v[34:35], v[162:163]
	v_mov_b64_e32 v[36:37], v[164:165]
	v_mov_b64_e32 v[38:39], v[166:167]
	v_mov_b64_e32 v[40:41], v[168:169]
	v_mov_b64_e32 v[42:43], v[170:171]
	v_mov_b64_e32 v[44:45], v[172:173]
	v_mov_b64_e32 v[54:55], v[46:47]
	v_mov_b64_e32 v[56:57], v[48:49]
.Lgc_ct2:
.LBB0_770:
	v_mfma_f32_32x32x16_bf16 v[2:17], v[2:5], v[50:53], 0
	s_mov_b32 s40, s57
	s_mov_b32 s41, s57
	s_mov_b32 s42, s57
	s_mov_b32 s43, s57
	s_mov_b32 s44, s57
	s_mov_b32 s45, s57
	s_mov_b32 s46, s57
	v_mfma_f32_32x32x16_bf16 v[2:17], v[18:21], v[74:77], v[2:17]
	s_mov_b32 s47, s57
	s_mov_b32 s48, s57
	s_mov_b32 s49, s57
	s_mov_b32 s50, s57
	s_mov_b32 s51, s57
	s_mov_b32 s52, s57
	s_mov_b32 s53, s57
	v_mfma_f32_32x32x16_bf16 v[2:17], v[22:25], v[66:69], v[2:17]
	s_mov_b32 s54, s57
	s_mov_b32 s55, s57
	v_mov_b64_e32 v[18:19], s[40:41]
	v_mov_b64_e32 v[20:21], s[42:43]
	v_mov_b64_e32 v[22:23], s[44:45]
	v_mov_b64_e32 v[24:25], s[46:47]
	v_mov_b64_e32 v[26:27], s[48:49]
	s_waitcnt vmcnt(0)
	v_mfma_f32_32x32x16_bf16 v[2:17], v[46:49], v[70:73], v[2:17]
	v_mov_b64_e32 v[28:29], s[50:51]
	v_mov_b64_e32 v[30:31], s[52:53]
	v_mov_b64_e32 v[32:33], s[54:55]
	s_and_b64 vcc, exec, s[34:35]
	s_cbranch_vccz .LBB0_836
	s_and_b64 vcc, exec, s[34:35]
	s_mov_b64 s[2:3], -1
	s_cbranch_vccz .LBB0_837
